# baseline (speedup 1.0000x reference)
; #define PG8_STAGE(bufoff, gbase, voff) do { _Pragma("unroll") for (int _i = 0; _i < 2; ++_i) \
;         __builtin_amdgcn_global_load_lds((const unsigned*)((const char*)(gbase) + (voff)[_i]), (PG8_LAS unsigned*)(lds + (bufoff) + ldsw + _i * 8192), 16, 0, 0); } while (0)
; #define PG8_WAIT_V(n) asm volatile("s_waitcnt vmcnt(" #n ")" ::: "memory")
; #define PG8_BAR __builtin_amdgcn_s_barrier()
; template <class Epi, class Sched, bool ALIGN_EPI = false, bool SP2 = false>
; __device__ __forceinline__ void gemm_phase(PG8_LAS unsigned char* lds, const Gemm g, const Sched& S, const Epi& E) {
;     ...
;         PG8_STAGE(PG8_SB(0, 0), cB, voffB); PG8_STAGE(PG8_SB(0, 1), cB + hstep, voffB); PG8_STAGE(PG8_SA(0, 0), cA, voffA); PG8_STAGE(PG8_SA(0, 1), cA + hstep, voffA);
;         if (wr == 1) PG8_BAR;
;         PG8_WAIT_V(2); PG8_BAR;
;         PG8_STAGE(PG8_SB(1, 0), cB + kstep, voffB); PG8_STAGE(PG8_SA(1, 0), cA + kstep, voffA); PG8_STAGE(PG8_SB(1, 1), cB + hstep + kstep, voffB);
;         PG8_WAIT_V(6); PG8_BAR;
.LBB0_343:
	s_lshl_b32 s4, s19, 5
	s_xor_b64 s[26:27], s[26:27], -1
	s_lshl_b32 s33, s18, 13
	s_and_b32 s19, s4, 0x60
	s_add_u32 s70, s58, 0x1b800000
	s_mov_b64 s[44:45], 0x80
	s_addc_u32 s71, s59, 0
	s_add_i32 m0, s98, 0x18000
	v_lshl_add_u64 v[10:11], v[10:11], 0, s[44:45]
	global_load_lds_dwordx4 v[10:11], off
	v_lshl_add_u64 v[6:7], v[6:7], 0, s[44:45]
	s_add_i32 m0, s98, 0x1a000
	s_add_i32 s72, s98, 0x8000
	global_load_lds_dwordx4 v[6:7], off
	v_lshl_add_u64 v[6:7], v[8:9], 0, s[44:45]
	s_mov_b32 m0, s72
	s_add_i32 s73, s98, 0xa000
	global_load_lds_dwordx4 v[6:7], off
	v_lshl_add_u64 v[6:7], v[12:13], 0, s[44:45]
	s_mov_b32 m0, s73
	v_lshl_add_u64 v[4:5], v[4:5], 0, s[44:45]
	global_load_lds_dwordx4 v[6:7], off
	s_add_i32 m0, s98, 0x1c000
	v_lshl_add_u64 v[2:3], v[2:3], 0, s[44:45]
	global_load_lds_dwordx4 v[4:5], off
	s_add_i32 m0, s98, 0x1e000
	s_cmpk_lt_u32 s5, 0x100
	global_load_lds_dwordx4 v[2:3], off
	s_waitcnt vmcnt(8)
	s_barrier
	v_mul_f32_e32 v3, v16, v17
	v_trunc_f32_e32 v3, v3
	v_cvt_u32_f32_e32 v4, v3
	v_fma_f32 v3, -v3, v15, v16
	s_cselect_b64 s[28:29], -1, 0
	s_lshr_b32 s91, s79, s12
	s_lshr_b32 s75, s52, 3
	v_cmp_ge_f32_e64 s[4:5], |v3|, v15
	v_readfirstlane_b32 s12, v4
	s_cmp_lg_u64 s[4:5], 0
	s_addc_u32 s4, s12, 0
	s_and_b32 s76, s4, 0x7ff
	v_cvt_f32_u32_e32 v3, s76
	v_lshlrev_b32_e32 v4, 2, v197
	v_lshl_or_b32 v2, v197, 6, v198
	v_and_b32_e32 v4, 32, v4
	v_bitop3_b32 v4, v2, s33, v4 bitop3:0xde
	v_rcp_iflag_f32_e32 v2, v3
	v_rcp_iflag_f32_e32 v3, v18
	s_sub_i32 s4, 0, s76
	s_waitcnt vmcnt(6)
	v_mul_f32_e32 v2, 0x4f7ffffe, v2
	v_cvt_u32_f32_e32 v2, v2
	v_lshl_or_b32 v144, s18, 6, v197
	v_lshl_or_b32 v145, s19, 7, v199
	v_add_u32_e32 v242, 0x10000, v145
	v_or_b32_e32 v146, s19, v192
	v_readfirstlane_b32 s5, v2
	v_mul_f32_e32 v2, 0x4f7ffffe, v14
	v_cvt_u32_f32_e32 v2, v2
	s_mul_i32 s4, s4, s5
	s_mul_hi_u32 s4, s5, s4
	s_add_i32 s77, s5, s4
	v_readfirstlane_b32 s5, v2
	v_mul_f32_e32 v2, 0x4f7ffffe, v3
	v_cvt_u32_f32_e32 v2, v2
	s_sub_i32 s4, 0, s7
	s_mul_i32 s4, s4, s5
	s_mul_hi_u32 s4, s5, s4
	s_add_i32 s69, s5, s4
	s_sub_i32 s4, 0, s78
	v_readfirstlane_b32 s5, v2
	s_mul_i32 s4, s4, s5
	v_add_lshl_u32 v2, v200, v19, 1
	v_mov_b32_e32 v3, v1
	s_mul_hi_u32 s4, s5, s4
	v_lshl_add_u64 v[136:137], s[16:17], 0, v[2:3]
	v_add_lshl_u32 v2, v200, v20, 1
	s_mov_b32 s18, 0
	s_add_i32 s5, s5, s4
	v_lshl_add_u64 v[138:139], s[16:17], 0, v[2:3]
	v_add_u32_e32 v147, 0, v4
	s_barrier
	s_branch .LBB0_346
